# v29: v27 + modulation GEMM blocks ordered column-slab-major so the five row tiles sharing a w_mod slab run on one XCD
# baseline (speedup 1.0000x reference)
; #define LAS __attribute__((address_space(3)))
; __device__ __forceinline__ void p0_prologue(Frame& F) {
;     ...
;     const int blk = F.vcu;
;     if (blk < 240) {
;         const int rt = blk / 48, sgp = blk % 48, r32 = lane & 31, hi = lane >> 5;
;         LAS float* SC = (LAS float*)(F.lds + RING_OFF);
;         for (int i = tid; i < 32768; i += NWAVES * 64) { const int j = i >> 10, k = i & 1023; int R = rt * 32 + j; R = R < 144 ? R : 143;
;             const float c = R < NBATCH ? c_prompt[R * DM + k] : c_sample[(R - NBATCH) * DM + k]; SC[k * 32 + j] = c / (1.f + expf(-c)); }
.LBB0_13:
	s_or_b64 exec, exec, s[4:5]
	s_mov_b64 s[4:5], s[0:1]
	v_mbcnt_lo_u32_b32 v1, -1, 0
	v_mbcnt_hi_u32_b32 v1, -1, v1
	s_load_dwordx2 s[10:11], s[4:5], 0xc8
	s_mov_b64 s[4:5], s[0:1]
	s_mov_b64 s[6:7], s[0:1]
	s_mov_b64 s[8:9], s[0:1]
	s_mov_b64 s[36:37], s[0:1]
	s_mov_b64 s[12:13], s[0:1]
	s_mov_b64 s[14:15], s[0:1]
	s_load_dwordx2 s[12:13], s[12:13], 0x58
	s_mov_b64 s[16:17], s[0:1]
	s_load_dwordx2 s[14:15], s[14:15], 0x68
	s_mov_b64 s[18:19], s[0:1]
	s_load_dwordx2 s[16:17], s[16:17], 0x78
	s_mov_b64 s[20:21], s[0:1]
	s_load_dwordx2 s[18:19], s[18:19], 0x80
	s_load_dwordx2 s[20:21], s[20:21], 0x88
	s_mov_b64 s[24:25], s[0:1]
	s_mov_b64 s[24:25], s[0:1]
	s_and_b32 s3, s76, 0xffffffc0
	v_add_u32_e32 v18, s3, v1
	s_mov_b64 s[24:25], s[0:1]
	s_cmpk_gt_i32 s81, 0xef
	v_writelane_b32 v237, s3, 4
	s_cbranch_scc1 .LBB0_69
	s_load_dwordx2 s[34:35], s[8:9], 0x40
	s_load_dwordx2 s[30:31], s[36:37], 0x48
	s_mul_i32 s3, s81, 0xcccd
	s_lshr_b32 s3, s3, 18
	s_mul_i32 s8, s3, 5
	s_sub_i32 s3, s81, s8
	s_mov_b32 s8, 0x8000
	v_cmp_gt_i32_e32 vcc, s8, v18
	s_and_saveexec_b64 s[36:37], vcc
	s_cbranch_execz .LBB0_30
	s_load_dwordx2 s[38:39], s[4:5], 0x30
	s_load_dwordx2 s[40:41], s[6:7], 0x38
	v_max_i32_e32 v2, 0x7e00, v18
	v_sub_u32_e32 v2, v2, v18
	s_movk_i32 s4, 0x1ff
	v_add_u32_e32 v2, 0x1ff, v2
	s_lshl_b32 s26, s3, 5
	v_cmp_lt_u32_e32 vcc, s4, v2
	s_mov_b64 s[4:5], -1
	v_mov_b32_e32 v6, v18
	s_and_saveexec_b64 s[42:43], vcc
	s_cbranch_execz .LBB0_23
	v_lshrrev_b32_e32 v6, 9, v2
	v_add_u32_e32 v19, 0x200, v18
	v_add_u32_e32 v7, -1, v6
	v_cmp_lt_u32_e32 vcc, 1, v7
	v_mov_b64_e32 v[2:3], v[18:19]
	s_and_saveexec_b64 s[44:45], vcc
	s_cbranch_execz .LBB0_20
	v_lshrrev_b32_e32 v2, 1, v7
	v_add_u32_e32 v2, 1, v2
	v_and_b32_e32 v8, -2, v2
	s_mov_b64 s[46:47], 0
	v_mov_b32_e32 v5, 0
	s_mov_b32 s27, 0xbfb8aa3b
	s_mov_b32 s28, 0x42ce8ed0
	s_mov_b32 s29, 0xc2b17218
	v_mov_b32_e32 v9, 0x7f800000
	v_mov_b64_e32 v[2:3], v[18:19]

; #define LAS __attribute__((address_space(3)))
; #define MOD_LOAD(W) do { _Pragma("unroll") for (int kk = 0; kk < 32; ++kk) { W[kk] = *wp; wp += 2 * NMOD; asm volatile("" : "+v"(wp)); } } while (0)
; __device__ __forceinline__ void p0_prologue(Frame& F) {
;     ...
;         const int s = F.wave & 3, kh = F.wave >> 2, col = (sgp * 4 + s) * 32 + r32;
;         f32x16 acc;
; #pragma unroll
;         for (int r = 0; r < 16; ++r) acc[r] = 0.f;
;         const float* wp = w_mod + (size_t)(kh * 512 + hi) * NMOD + col;
;         const LAS float* ap = SC + (kh * 512 + hi) * 32 + r32;
;     ...
;         float wA[32], wB[32];
;         MOD_LOAD(wA);
.LBB0_30:
	s_or_b64 exec, exec, s[36:37]
	s_mul_i32 s4, s81, 0xcccd
	s_lshr_b32 s4, s4, 18
	s_bfe_u32 s6, s76, 0x20006
	s_lshl_b32 s4, s4, 7
	s_lshl_b32 s5, s6, 5
	v_and_b32_e32 v4, 31, v1
	v_ashrrev_i32_e32 v19, 5, v1
	s_or_b32 s4, s4, s5
	s_lshr_b32 s7, s76, 8
	v_or_b32_e32 v20, s4, v4
	v_lshl_add_u32 v5, s7, 9, v19
	s_movk_i32 s4, 0x6000
	s_waitcnt lgkmcnt(0)
	v_mov_b64_e32 v[2:3], s[34:35]
	v_mad_i64_i32 v[2:3], s[4:5], v5, s4, v[2:3]
	v_ashrrev_i32_e32 v21, 31, v20
	v_lshl_add_u64 v[2:3], v[20:21], 2, v[2:3]
	s_mov_b64 s[4:5], 0xc000
	s_barrier
	global_load_dword v24, v[2:3], off
	v_lshl_add_u64 v[2:3], v[2:3], 0, s[4:5]
	flat_load_dword v25, v[2:3]
	v_lshl_add_u64 v[2:3], v[2:3], 0, s[4:5]
	flat_load_dword v26, v[2:3]
	v_lshl_add_u64 v[2:3], v[2:3], 0, s[4:5]
	flat_load_dword v27, v[2:3]
	v_lshl_add_u64 v[2:3], v[2:3], 0, s[4:5]
	flat_load_dword v29, v[2:3]
	v_lshl_add_u64 v[2:3], v[2:3], 0, s[4:5]
	flat_load_dword v31, v[2:3]
	v_lshl_add_u64 v[2:3], v[2:3], 0, s[4:5]
	flat_load_dword v33, v[2:3]
	v_lshl_add_u64 v[2:3], v[2:3], 0, s[4:5]
	flat_load_dword v35, v[2:3]
	v_lshl_add_u64 v[2:3], v[2:3], 0, s[4:5]
	flat_load_dword v32, v[2:3]
	v_lshl_add_u64 v[2:3], v[2:3], 0, s[4:5]
	flat_load_dword v36, v[2:3]
	v_lshl_add_u64 v[2:3], v[2:3], 0, s[4:5]
	flat_load_dword v37, v[2:3]
	v_lshl_add_u64 v[2:3], v[2:3], 0, s[4:5]
	flat_load_dword v39, v[2:3]
	v_lshl_add_u64 v[2:3], v[2:3], 0, s[4:5]
	flat_load_dword v40, v[2:3]
	v_lshl_add_u64 v[2:3], v[2:3], 0, s[4:5]
	flat_load_dword v42, v[2:3]
	v_lshl_add_u64 v[2:3], v[2:3], 0, s[4:5]
	flat_load_dword v43, v[2:3]
	v_lshl_add_u64 v[2:3], v[2:3], 0, s[4:5]
	flat_load_dword v46, v[2:3]
	v_lshl_add_u64 v[2:3], v[2:3], 0, s[4:5]
	flat_load_dword v44, v[2:3]
	v_lshl_add_u64 v[2:3], v[2:3], 0, s[4:5]
	flat_load_dword v47, v[2:3]
	v_lshl_add_u64 v[2:3], v[2:3], 0, s[4:5]
	flat_load_dword v48, v[2:3]
	v_lshl_add_u64 v[2:3], v[2:3], 0, s[4:5]
	flat_load_dword v50, v[2:3]
	v_lshl_add_u64 v[2:3], v[2:3], 0, s[4:5]
	flat_load_dword v51, v[2:3]
	v_lshl_add_u64 v[2:3], v[2:3], 0, s[4:5]
	flat_load_dword v53, v[2:3]
	v_lshl_add_u64 v[2:3], v[2:3], 0, s[4:5]
	flat_load_dword v55, v[2:3]
	v_lshl_add_u64 v[2:3], v[2:3], 0, s[4:5]
	flat_load_dword v56, v[2:3]
	v_lshl_add_u64 v[2:3], v[2:3], 0, s[4:5]
	flat_load_dword v54, v[2:3]
	v_lshl_add_u64 v[2:3], v[2:3], 0, s[4:5]
	flat_load_dword v52, v[2:3]
	v_lshl_add_u64 v[2:3], v[2:3], 0, s[4:5]
	flat_load_dword v49, v[2:3]
	v_lshl_add_u64 v[2:3], v[2:3], 0, s[4:5]
	flat_load_dword v45, v[2:3]
	v_lshl_add_u64 v[2:3], v[2:3], 0, s[4:5]
	flat_load_dword v41, v[2:3]
	v_lshl_add_u64 v[2:3], v[2:3], 0, s[4:5]
	flat_load_dword v38, v[2:3]
	v_lshl_add_u64 v[2:3], v[2:3], 0, s[4:5]
	flat_load_dword v34, v[2:3]
	v_lshl_add_u64 v[2:3], v[2:3], 0, s[4:5]
	flat_load_dword v30, v[2:3]
	v_lshlrev_b32_e32 v5, 7, v5
	v_lshl_add_u64 v[22:23], v[2:3], 0, s[4:5]
	v_lshlrev_b32_e32 v2, 2, v4
	v_add3_u32 v28, 0, v5, v2
	v_mov_b32_e32 v2, 0
	s_movk_i32 s8, 0xffc0
	v_mov_b32_e32 v3, v2
	v_mov_b32_e32 v4, v2
	v_mov_b32_e32 v5, v2
	v_mov_b32_e32 v6, v2
	v_mov_b32_e32 v7, v2
	v_mov_b32_e32 v8, v2
	v_mov_b32_e32 v9, v2
	v_mov_b32_e32 v10, v2
	v_mov_b32_e32 v11, v2
	v_mov_b32_e32 v12, v2
	v_mov_b32_e32 v13, v2
	v_mov_b32_e32 v14, v2
	v_mov_b32_e32 v15, v2
	v_mov_b32_e32 v16, v2
	v_mov_b32_e32 v17, v2
